# v64 + tile-boundary wait relaxation (P1,P3,P8): next tile's first-segment DMAs issued at K-loop exit, first K-iteration's segment 1-3 vmcnt waits allow the epilogue's stores to stay in flight
# speedup vs baseline: 1.0087x; 1.0087x over previous
; #define PG8_STAGE(bufoff, gbase, voff) do { _Pragma("unroll") for (int _i = 0; _i < 2; ++_i) \
;         __builtin_amdgcn_global_load_lds((const unsigned*)((const char*)(gbase) + (voff)[_i]), (PG8_LAS unsigned*)(lds + (bufoff) + ldsw + _i * 8192), 16, 0, 0); } while (0)
; #define PG8_LDA(dst, b, h) do { _Pragma("unroll") for (int m = 0; m < 4; ++m) _Pragma("unroll") for (int k = 0; k < 2; ++k) dst[m][k] = *(const PG8_LAS bf16x8*)(lds + PG8_SA(b, h) + aoff + m * 2048 + k * 1024); } while (0)
; #define PG8_LDB(dst, b, h) do { _Pragma("unroll") for (int n = 0; n < 2; ++n) _Pragma("unroll") for (int k = 0; k < 2; ++k) dst[n][k] = *(const PG8_LAS bf16x8*)(lds + PG8_SB(b, h) + boff + n * 2048 + k * 1024); } while (0)
; #define PG8_MMA(ai, bj, At, Bt) do { __builtin_amdgcn_s_setprio(1); _Pragma("unroll") for (int m = 0; m < 4; ++m) _Pragma("unroll") for (int n = 0; n < 2; ++n) _Pragma("unroll") for (int k = 0; k < 2; ++k) \
;         acc[ai][bj][m][n] = __builtin_amdgcn_mfma_f32_16x16x32_bf16(Bt[n][k], At[m][k], acc[ai][bj][m][n], 0, 0, 0); __builtin_amdgcn_s_setprio(0); } while (0)
; #define PG8_WAIT_V(n) asm volatile("s_waitcnt vmcnt(" #n ")" ::: "memory")
; #define PG8_WAIT_L(n) asm volatile("s_waitcnt lgkmcnt(" #n ")" ::: "memory")
; #define PG8_BAR __builtin_amdgcn_s_barrier()
; #define PG8_SCHED __builtin_amdgcn_sched_barrier(0)
; template <class Epi, class Sched, bool ALIGN_EPI = false, bool SP2 = false>
; __device__ __forceinline__ void gemm_phase(PG8_LAS unsigned char* lds, const Gemm g, const Sched& S, const Epi& E, int wid) {
;     ...
;         for (int t = 0; t < nt; t += 2) {
;             const bool last = (t == nt - 2);
;             const char* a1 = cA + (size_t)(t + 1) * kstep;
;             const char* a2 = last ? nA : cA + (size_t)(t + 2) * kstep; const char* b2 = last ? nB : cB + (size_t)(t + 2) * kstep;
;             const char* a3 = a2 + kstep; const char* b3 = b2 + kstep;
;             if (last && has_next) S.a_ready(nxt);
;             if constexpr (SP2) {
;             PG8_LDB(B0, 0, 0); PG8_LDB(B1, 0, 1); PG8_SCHED; PG8_LDA(At, 0, 0); PG8_STAGE(PG8_SA(1, 1), a1 + hstepA, voffA);
;             PG8_WAIT_V(8); PG8_WAIT_L(0); PG8_BAR; PG8_MMA(0, 0, At, B0); PG8_MMA(0, 1, At, B1); PG8_BAR; PG8_SCHED;
.LBB0_233:
	ds_read_b128 v[144:147], v155
	ds_read_b128 v[148:151], v155 offset:1024
	ds_read_b128 v[160:163], v155 offset:2048
	ds_read_b128 v[164:167], v155 offset:3072
	ds_read_b128 v[168:171], v156
	ds_read_b128 v[172:175], v156 offset:1024
	ds_read_b128 v[176:179], v156 offset:2048
	ds_read_b128 v[180:183], v156 offset:3072
	s_add_u32 s4, s48, 0x100
	s_addc_u32 s5, s49, 0
	s_add_u32 s98, s48, 0x80
	s_addc_u32 s99, s49, 0
	s_add_u32 s100, s48, 0x104080
	s_addc_u32 s101, s49, 0
	s_cmp_eq_u32 s66, 60
	s_cselect_b32 s53, s45, s5
	s_cselect_b32 s52, s44, s4
	s_cselect_b32 s51, s47, s65
	s_cselect_b32 s50, s46, s64
	s_add_i32 m0, s23, 0xc000
	ds_read_b128 v[184:187], v157
	ds_read_b128 v[188:191], v157 offset:1024
	ds_read_b128 v[192:195], v157 offset:2048
	ds_read_b128 v[196:199], v157 offset:3072
	ds_read_b128 v[200:203], v157 offset:4096
	ds_read_b128 v[204:207], v157 offset:5120
	ds_read_b128 v[208:211], v157 offset:6144
	ds_read_b128 v[212:215], v157 offset:7168
	global_load_lds_dwordx4 v134, s[100:101]
	s_add_i32 m0, s23, 0xe000
	s_nop 0
	global_load_lds_dwordx4 v130, s[100:101]
	s_mov_b32 m0, s55
	s_nop 0
	global_load_lds_dwordx4 v134, s[98:99]
	s_mov_b32 m0, s56
	s_nop 0
	global_load_lds_dwordx4 v130, s[98:99]
	s_cmp_lg_u32 s66, -2
	s_cbranch_scc1 .Lrx0_0_std
	s_cmp_eq_u32 s54, 1
	s_cbranch_scc1 .Lrx0_0_std
	s_waitcnt vmcnt(16)
	s_branch .Lrx0_0_done

; #define PG8_STAGE(bufoff, gbase, voff) do { _Pragma("unroll") for (int _i = 0; _i < 2; ++_i) \
;         __builtin_amdgcn_global_load_lds((const unsigned*)((const char*)(gbase) + (voff)[_i]), (PG8_LAS unsigned*)(lds + (bufoff) + ldsw + _i * 8192), 16, 0, 0); } while (0)
; #define PG8_STAGE_NT(bufoff, gbase, voff) do { _Pragma("unroll") for (int _i = 0; _i < 2; ++_i) \
;         __builtin_amdgcn_global_load_lds((const unsigned*)((const char*)(gbase) + (voff)[_i]), (PG8_LAS unsigned*)(lds + (bufoff) + ldsw + _i * 8192), 16, 0, PG8_B_AUX); } while (0)
; #define PG8_LDA(dst, b, h) do { _Pragma("unroll") for (int m = 0; m < 4; ++m) _Pragma("unroll") for (int k = 0; k < 2; ++k) dst[m][k] = *(const PG8_LAS bf16x8*)(lds + PG8_SA(b, h) + aoff + m * 2048 + k * 1024); } while (0)
; #define PG8_LDB(dst, b, h) do { _Pragma("unroll") for (int n = 0; n < 2; ++n) _Pragma("unroll") for (int k = 0; k < 2; ++k) dst[n][k] = *(const PG8_LAS bf16x8*)(lds + PG8_SB(b, h) + boff + n * 2048 + k * 1024); } while (0)
; #define PG8_MMA(ai, bj, At, Bt) do { __builtin_amdgcn_s_setprio(1); _Pragma("unroll") for (int m = 0; m < 4; ++m) _Pragma("unroll") for (int n = 0; n < 2; ++n) _Pragma("unroll") for (int k = 0; k < 2; ++k) \
;         acc[ai][bj][m][n] = __builtin_amdgcn_mfma_f32_16x16x32_bf16(Bt[n][k], At[m][k], acc[ai][bj][m][n], 0, 0, 0); __builtin_amdgcn_s_setprio(0); } while (0)
; #define PG8_WAIT_V(n) asm volatile("s_waitcnt vmcnt(" #n ")" ::: "memory")
; #define PG8_WAIT_L(n) asm volatile("s_waitcnt lgkmcnt(" #n ")" ::: "memory")
; #define PG8_BAR __builtin_amdgcn_s_barrier()
; #define PG8_SCHED __builtin_amdgcn_sched_barrier(0)
; template <class Epi, class Sched, bool ALIGN_EPI = false, bool SP2 = false>
; __device__ __forceinline__ void gemm_phase(PG8_LAS unsigned char* lds, const Gemm g, const Sched& S, const Epi& E, int wid) {
;     ...
;             PG8_WAIT_V(8); PG8_WAIT_L(0); PG8_BAR; PG8_MMA(0, 0, At, B0); PG8_MMA(0, 1, At, B1); PG8_BAR; PG8_SCHED;
;             PG8_LDA(At, 0, 1); PG8_STAGE_NT(PG8_SB(0, 0), b2, voffB); PG8_STAGE_NT(PG8_SB(0, 1), b2 + hstepB, voffB); PG8_STAGE(PG8_SA(0, 0), a2, voffA);
;             PG8_WAIT_V(8); PG8_WAIT_L(0); PG8_BAR; PG8_MMA(1, 0, At, B0); PG8_MMA(1, 1, At, B1); PG8_BAR; PG8_SCHED;
;             PG8_LDB(B0, 1, 0); PG8_LDB(B1, 1, 1); PG8_SCHED; PG8_LDA(At, 1, 0); PG8_STAGE(PG8_SA(0, 1), a2 + hstepA, voffA);
.Lrx0_0_done:
	s_waitcnt lgkmcnt(0)
	s_barrier
	s_waitcnt lgkmcnt(0)
	v_mfma_f32_16x16x32_bf16 v[112:115], v[144:147], v[184:187], v[112:115]
	v_mfma_f32_16x16x32_bf16 v[108:111], v[160:163], v[184:187], v[108:111]
	v_mfma_f32_16x16x32_bf16 v[104:107], v[144:147], v[192:195], v[104:107]
	v_mfma_f32_16x16x32_bf16 v[100:103], v[160:163], v[192:195], v[100:103]
	v_mfma_f32_16x16x32_bf16 v[92:95], v[144:147], v[200:203], v[92:95]
	v_mfma_f32_16x16x32_bf16 v[84:87], v[160:163], v[200:203], v[84:87]
	v_mfma_f32_16x16x32_bf16 v[76:79], v[144:147], v[208:211], v[76:79]
	v_mfma_f32_16x16x32_bf16 v[68:71], v[160:163], v[208:211], v[68:71]
	v_mfma_f32_16x16x32_bf16 v[112:115], v[148:151], v[188:191], v[112:115]
	v_mfma_f32_16x16x32_bf16 v[108:111], v[164:167], v[188:191], v[108:111]
	v_mfma_f32_16x16x32_bf16 v[104:107], v[148:151], v[196:199], v[104:107]
	v_mfma_f32_16x16x32_bf16 v[100:103], v[164:167], v[196:199], v[100:103]
	v_mfma_f32_16x16x32_bf16 v[92:95], v[148:151], v[204:207], v[92:95]
	v_mfma_f32_16x16x32_bf16 v[84:87], v[164:167], v[204:207], v[84:87]
	v_mfma_f32_16x16x32_bf16 v[76:79], v[148:151], v[212:215], v[76:79]
	v_mfma_f32_16x16x32_bf16 v[68:71], v[164:167], v[212:215], v[68:71]
	v_mfma_f32_16x16x32_bf16 v[124:127], v[168:171], v[184:187], v[124:127]
	v_mfma_f32_16x16x32_bf16 v[120:123], v[176:179], v[184:187], v[120:123]
	v_mfma_f32_16x16x32_bf16 v[116:119], v[168:171], v[192:195], v[116:119]
	v_mfma_f32_16x16x32_bf16 v[96:99], v[176:179], v[192:195], v[96:99]
	v_mfma_f32_16x16x32_bf16 v[88:91], v[168:171], v[200:203], v[88:91]
	v_mfma_f32_16x16x32_bf16 v[80:83], v[176:179], v[200:203], v[80:83]
	v_mfma_f32_16x16x32_bf16 v[72:75], v[168:171], v[208:211], v[72:75]
	v_mfma_f32_16x16x32_bf16 v[64:67], v[176:179], v[208:211], v[64:67]
	v_mfma_f32_16x16x32_bf16 v[124:127], v[172:175], v[188:191], v[124:127]
	v_mfma_f32_16x16x32_bf16 v[120:123], v[180:183], v[188:191], v[120:123]
	v_mfma_f32_16x16x32_bf16 v[116:119], v[172:175], v[196:199], v[116:119]
	v_mfma_f32_16x16x32_bf16 v[96:99], v[180:183], v[196:199], v[96:99]
	v_mfma_f32_16x16x32_bf16 v[88:91], v[172:175], v[204:207], v[88:91]
	v_mfma_f32_16x16x32_bf16 v[80:83], v[180:183], v[204:207], v[80:83]
	v_mfma_f32_16x16x32_bf16 v[72:75], v[172:175], v[212:215], v[72:75]
	v_mfma_f32_16x16x32_bf16 v[64:67], v[180:183], v[212:215], v[64:67]
	s_barrier
	s_add_i32 s48, s58, s17
	s_mov_b32 m0, s48
	ds_read_b128 v[184:187], v157 offset:16384
	ds_read_b128 v[188:191], v157 offset:17408
	ds_read_b128 v[192:195], v157 offset:18432
	ds_read_b128 v[196:199], v157 offset:19456
	ds_read_b128 v[200:203], v157 offset:20480
	ds_read_b128 v[204:207], v157 offset:21504
	ds_read_b128 v[208:211], v157 offset:22528
	ds_read_b128 v[212:215], v157 offset:23552
	global_load_lds_dwordx4 v132, s[50:51]
	s_add_i32 m0, s48, 0x2000
	s_add_u32 s48, s50, 0x104000
	s_addc_u32 s49, s51, 0
	s_add_i32 s67, s59, s17
	global_load_lds_dwordx4 v128, s[50:51]
	s_mov_b32 m0, s67
	s_nop 0
	global_load_lds_dwordx4 v132, s[48:49]
	s_add_i32 m0, s67, 0x2000
	s_nop 0
	global_load_lds_dwordx4 v128, s[48:49]
	s_cmp_lg_u32 s66, -2
	s_cbranch_scc1 .Lrx0_1_std
	s_cmp_eq_u32 s54, 1
	s_cbranch_scc1 .Lrx0_1_std
	s_waitcnt vmcnt(16)
	s_branch .Lrx0_1_done
.Lrx0_1_std:
	s_waitcnt vmcnt(4)
.Lrx0_1_done:
	s_waitcnt lgkmcnt(0)
	s_barrier
	s_waitcnt lgkmcnt(0)
	v_mfma_f32_16x16x32_bf16 v[60:63], v[144:147], v[184:187], v[60:63]
	v_mfma_f32_16x16x32_bf16 v[52:55], v[160:163], v[184:187], v[52:55]
	v_mfma_f32_16x16x32_bf16 v[44:47], v[144:147], v[192:195], v[44:47]
	v_mfma_f32_16x16x32_bf16 v[36:39], v[160:163], v[192:195], v[36:39]
	v_mfma_f32_16x16x32_bf16 v[28:31], v[144:147], v[200:203], v[28:31]
	v_mfma_f32_16x16x32_bf16 v[20:23], v[160:163], v[200:203], v[20:23]
	v_mfma_f32_16x16x32_bf16 v[12:15], v[144:147], v[208:211], v[12:15]
	v_mfma_f32_16x16x32_bf16 v[4:7], v[160:163], v[208:211], v[4:7]
	v_mfma_f32_16x16x32_bf16 v[60:63], v[148:151], v[188:191], v[60:63]
	v_mfma_f32_16x16x32_bf16 v[52:55], v[164:167], v[188:191], v[52:55]
	v_mfma_f32_16x16x32_bf16 v[44:47], v[148:151], v[196:199], v[44:47]
	v_mfma_f32_16x16x32_bf16 v[36:39], v[164:167], v[196:199], v[36:39]
	v_mfma_f32_16x16x32_bf16 v[28:31], v[148:151], v[204:207], v[28:31]
	v_mfma_f32_16x16x32_bf16 v[20:23], v[164:167], v[204:207], v[20:23]
	v_mfma_f32_16x16x32_bf16 v[12:15], v[148:151], v[212:215], v[12:15]
	v_mfma_f32_16x16x32_bf16 v[4:7], v[164:167], v[212:215], v[4:7]
	v_mfma_f32_16x16x32_bf16 v[56:59], v[168:171], v[184:187], v[56:59]
	v_mfma_f32_16x16x32_bf16 v[48:51], v[176:179], v[184:187], v[48:51]
	v_mfma_f32_16x16x32_bf16 v[40:43], v[168:171], v[192:195], v[40:43]
	v_mfma_f32_16x16x32_bf16 v[32:35], v[176:179], v[192:195], v[32:35]
	v_mfma_f32_16x16x32_bf16 v[24:27], v[168:171], v[200:203], v[24:27]
	v_mfma_f32_16x16x32_bf16 v[16:19], v[176:179], v[200:203], v[16:19]
	v_mfma_f32_16x16x32_bf16 v[8:11], v[168:171], v[208:211], v[8:11]
	v_mfma_f32_16x16x32_bf16 v[0:3], v[176:179], v[208:211], v[0:3]
	v_mfma_f32_16x16x32_bf16 v[56:59], v[172:175], v[188:191], v[56:59]
	v_mfma_f32_16x16x32_bf16 v[48:51], v[180:183], v[188:191], v[48:51]
	v_mfma_f32_16x16x32_bf16 v[40:43], v[172:175], v[196:199], v[40:43]
	v_mfma_f32_16x16x32_bf16 v[32:35], v[180:183], v[196:199], v[32:35]
	v_mfma_f32_16x16x32_bf16 v[24:27], v[172:175], v[204:207], v[24:27]
	v_mfma_f32_16x16x32_bf16 v[16:19], v[180:183], v[204:207], v[16:19]
	v_mfma_f32_16x16x32_bf16 v[8:11], v[172:175], v[212:215], v[8:11]
	v_mfma_f32_16x16x32_bf16 v[0:3], v[180:183], v[212:215], v[0:3]
	s_barrier
	s_add_i32 s67, 0, 0x18000
	v_add_u32_e32 v159, s67, v153
	s_add_i32 s68, 0, 0x1c000
	ds_read_b128 v[144:147], v159
	ds_read_b128 v[148:151], v159 offset:1024
	ds_read_b128 v[160:163], v159 offset:2048
	ds_read_b128 v[164:167], v159 offset:3072
	v_add_u32_e32 v159, s68, v153
	ds_read_b128 v[168:171], v159
	ds_read_b128 v[172:175], v159 offset:1024
	ds_read_b128 v[176:179], v159 offset:2048
	ds_read_b128 v[180:183], v159 offset:3072
	s_add_u32 s48, s52, 0x104000
	s_addc_u32 s49, s53, 0
	s_mov_b32 m0, s25
	ds_read_b128 v[184:187], v157 offset:32768
	ds_read_b128 v[188:191], v157 offset:33792
	ds_read_b128 v[192:195], v157 offset:34816
	ds_read_b128 v[196:199], v157 offset:35840
	ds_read_b128 v[200:203], v157 offset:36864
	ds_read_b128 v[204:207], v157 offset:37888
	ds_read_b128 v[208:211], v157 offset:38912
	ds_read_b128 v[212:215], v157 offset:39936
	global_load_lds_dwordx4 v134, s[48:49]
	s_mov_b32 m0, s29
	s_nop 0
	global_load_lds_dwordx4 v130, s[48:49]
	s_mov_b32 m0, s23
	s_nop 0
	global_load_lds_dwordx4 v134, s[52:53]
	s_mov_b32 m0, s24
	s_nop 0
	global_load_lds_dwordx4 v130, s[52:53]
	s_cmp_lg_u32 s66, -2
	s_cbranch_scc1 .Lrx0_2_std
	s_cmp_eq_u32 s54, 1
	s_cbranch_scc1 .Lrx0_2_std
	s_waitcnt vmcnt(20)
	s_branch .Lrx0_2_done

; #define PG8_STAGE(bufoff, gbase, voff) do { _Pragma("unroll") for (int _i = 0; _i < 2; ++_i) \
;         __builtin_amdgcn_global_load_lds((const unsigned*)((const char*)(gbase) + (voff)[_i]), (PG8_LAS unsigned*)(lds + (bufoff) + ldsw + _i * 8192), 16, 0, 0); } while (0)
; #define PG8_STAGE_NT(bufoff, gbase, voff) do { _Pragma("unroll") for (int _i = 0; _i < 2; ++_i) \
;         __builtin_amdgcn_global_load_lds((const unsigned*)((const char*)(gbase) + (voff)[_i]), (PG8_LAS unsigned*)(lds + (bufoff) + ldsw + _i * 8192), 16, 0, PG8_B_AUX); } while (0)
; #define PG8_LDA(dst, b, h) do { _Pragma("unroll") for (int m = 0; m < 4; ++m) _Pragma("unroll") for (int k = 0; k < 2; ++k) dst[m][k] = *(const PG8_LAS bf16x8*)(lds + PG8_SA(b, h) + aoff + m * 2048 + k * 1024); } while (0)
; #define PG8_MMA(ai, bj, At, Bt) do { __builtin_amdgcn_s_setprio(1); _Pragma("unroll") for (int m = 0; m < 4; ++m) _Pragma("unroll") for (int n = 0; n < 2; ++n) _Pragma("unroll") for (int k = 0; k < 2; ++k) \
;         acc[ai][bj][m][n] = __builtin_amdgcn_mfma_f32_16x16x32_bf16(Bt[n][k], At[m][k], acc[ai][bj][m][n], 0, 0, 0); __builtin_amdgcn_s_setprio(0); } while (0)
; #define PG8_WAIT_V(n) asm volatile("s_waitcnt vmcnt(" #n ")" ::: "memory")
; #define PG8_WAIT_L(n) asm volatile("s_waitcnt lgkmcnt(" #n ")" ::: "memory")
; #define PG8_BAR __builtin_amdgcn_s_barrier()
; #define PG8_SCHED __builtin_amdgcn_sched_barrier(0)
; template <class Epi, class Sched, bool ALIGN_EPI = false, bool SP2 = false>
; __device__ __forceinline__ void gemm_phase(PG8_LAS unsigned char* lds, const Gemm g, const Sched& S, const Epi& E, int wid) {
;     ...
;             PG8_WAIT_V(8); PG8_WAIT_L(0); PG8_BAR; PG8_MMA(0, 0, At, B0); PG8_MMA(0, 1, At, B1); PG8_BAR; PG8_SCHED;
;             PG8_LDA(At, 1, 1); PG8_STAGE_NT(PG8_SB(1, 0), b3, voffB); PG8_STAGE_NT(PG8_SB(1, 1), b3 + hstepB, voffB); PG8_STAGE(PG8_SA(1, 0), a3, voffA);
;             PG8_WAIT_V(8); PG8_WAIT_L(0); PG8_BAR; PG8_MMA(1, 0, At, B0); PG8_MMA(1, 1, At, B1); PG8_BAR; PG8_SCHED;
.Lrx0_2_done:
	s_waitcnt lgkmcnt(0)
	s_barrier
	s_waitcnt lgkmcnt(0)
	v_mfma_f32_16x16x32_bf16 v[112:115], v[144:147], v[184:187], v[112:115]
	v_mfma_f32_16x16x32_bf16 v[108:111], v[160:163], v[184:187], v[108:111]
	v_mfma_f32_16x16x32_bf16 v[104:107], v[144:147], v[192:195], v[104:107]
	v_mfma_f32_16x16x32_bf16 v[100:103], v[160:163], v[192:195], v[100:103]
	v_mfma_f32_16x16x32_bf16 v[92:95], v[144:147], v[200:203], v[92:95]
	v_mfma_f32_16x16x32_bf16 v[84:87], v[160:163], v[200:203], v[84:87]
	v_mfma_f32_16x16x32_bf16 v[76:79], v[144:147], v[208:211], v[76:79]
	v_mfma_f32_16x16x32_bf16 v[68:71], v[160:163], v[208:211], v[68:71]
	v_mfma_f32_16x16x32_bf16 v[112:115], v[148:151], v[188:191], v[112:115]
	v_mfma_f32_16x16x32_bf16 v[108:111], v[164:167], v[188:191], v[108:111]
	v_mfma_f32_16x16x32_bf16 v[104:107], v[148:151], v[196:199], v[104:107]
	v_mfma_f32_16x16x32_bf16 v[100:103], v[164:167], v[196:199], v[100:103]
	v_mfma_f32_16x16x32_bf16 v[92:95], v[148:151], v[204:207], v[92:95]
	v_mfma_f32_16x16x32_bf16 v[84:87], v[164:167], v[204:207], v[84:87]
	v_mfma_f32_16x16x32_bf16 v[76:79], v[148:151], v[212:215], v[76:79]
	v_mfma_f32_16x16x32_bf16 v[68:71], v[164:167], v[212:215], v[68:71]
	v_mfma_f32_16x16x32_bf16 v[124:127], v[168:171], v[184:187], v[124:127]
	v_mfma_f32_16x16x32_bf16 v[120:123], v[176:179], v[184:187], v[120:123]
	v_mfma_f32_16x16x32_bf16 v[116:119], v[168:171], v[192:195], v[116:119]
	v_mfma_f32_16x16x32_bf16 v[96:99], v[176:179], v[192:195], v[96:99]
	v_mfma_f32_16x16x32_bf16 v[88:91], v[168:171], v[200:203], v[88:91]
	v_mfma_f32_16x16x32_bf16 v[80:83], v[176:179], v[200:203], v[80:83]
	v_mfma_f32_16x16x32_bf16 v[72:75], v[168:171], v[208:211], v[72:75]
	v_mfma_f32_16x16x32_bf16 v[64:67], v[176:179], v[208:211], v[64:67]
	v_mfma_f32_16x16x32_bf16 v[124:127], v[172:175], v[188:191], v[124:127]
	v_mfma_f32_16x16x32_bf16 v[120:123], v[180:183], v[188:191], v[120:123]
	v_mfma_f32_16x16x32_bf16 v[116:119], v[172:175], v[196:199], v[116:119]
	v_mfma_f32_16x16x32_bf16 v[96:99], v[180:183], v[196:199], v[96:99]
	v_mfma_f32_16x16x32_bf16 v[88:91], v[172:175], v[204:207], v[88:91]
	v_mfma_f32_16x16x32_bf16 v[80:83], v[180:183], v[204:207], v[80:83]
	v_mfma_f32_16x16x32_bf16 v[72:75], v[172:175], v[212:215], v[72:75]
	v_mfma_f32_16x16x32_bf16 v[64:67], v[180:183], v[212:215], v[64:67]
	s_barrier
	s_add_i32 s48, s67, s17
	s_mov_b32 m0, s48
	s_add_u32 s98, s50, 0x80
	s_addc_u32 s99, s51, 0
	ds_read_b128 v[184:187], v157 offset:49152
	ds_read_b128 v[188:191], v157 offset:50176
	ds_read_b128 v[192:195], v157 offset:51200
	ds_read_b128 v[196:199], v157 offset:52224
	ds_read_b128 v[200:203], v157 offset:53248
	ds_read_b128 v[204:207], v157 offset:54272
	ds_read_b128 v[208:211], v157 offset:55296
	ds_read_b128 v[212:215], v157 offset:56320
	global_load_lds_dwordx4 v132, s[98:99]
	s_add_i32 m0, s48, 0x2000
	s_add_u32 s48, s50, 0x104080
	s_addc_u32 s49, s51, 0
	s_add_i32 s50, s68, s17
	global_load_lds_dwordx4 v128, s[98:99]
	s_mov_b32 m0, s50
	s_nop 0
	global_load_lds_dwordx4 v132, s[48:49]
	s_add_i32 m0, s50, 0x2000
	s_nop 0
	global_load_lds_dwordx4 v128, s[48:49]
	s_waitcnt vmcnt(4)
	s_waitcnt lgkmcnt(0)
	s_barrier
	s_waitcnt lgkmcnt(0)
	v_mfma_f32_16x16x32_bf16 v[60:63], v[144:147], v[184:187], v[60:63]
	v_mfma_f32_16x16x32_bf16 v[52:55], v[160:163], v[184:187], v[52:55]
	v_mfma_f32_16x16x32_bf16 v[44:47], v[144:147], v[192:195], v[44:47]
	v_mfma_f32_16x16x32_bf16 v[36:39], v[160:163], v[192:195], v[36:39]
	v_mfma_f32_16x16x32_bf16 v[28:31], v[144:147], v[200:203], v[28:31]
	v_mfma_f32_16x16x32_bf16 v[20:23], v[160:163], v[200:203], v[20:23]
	v_mfma_f32_16x16x32_bf16 v[12:15], v[144:147], v[208:211], v[12:15]
	v_mfma_f32_16x16x32_bf16 v[4:7], v[160:163], v[208:211], v[4:7]
	v_mfma_f32_16x16x32_bf16 v[60:63], v[148:151], v[188:191], v[60:63]
	v_mfma_f32_16x16x32_bf16 v[52:55], v[164:167], v[188:191], v[52:55]
	v_mfma_f32_16x16x32_bf16 v[44:47], v[148:151], v[196:199], v[44:47]
	v_mfma_f32_16x16x32_bf16 v[36:39], v[164:167], v[196:199], v[36:39]
	v_mfma_f32_16x16x32_bf16 v[28:31], v[148:151], v[204:207], v[28:31]
	v_mfma_f32_16x16x32_bf16 v[20:23], v[164:167], v[204:207], v[20:23]
	v_mfma_f32_16x16x32_bf16 v[12:15], v[148:151], v[212:215], v[12:15]
	v_mfma_f32_16x16x32_bf16 v[4:7], v[164:167], v[212:215], v[4:7]
	v_mfma_f32_16x16x32_bf16 v[56:59], v[168:171], v[184:187], v[56:59]
	v_mfma_f32_16x16x32_bf16 v[48:51], v[176:179], v[184:187], v[48:51]
	v_mfma_f32_16x16x32_bf16 v[40:43], v[168:171], v[192:195], v[40:43]
	v_mfma_f32_16x16x32_bf16 v[32:35], v[176:179], v[192:195], v[32:35]
	v_mfma_f32_16x16x32_bf16 v[24:27], v[168:171], v[200:203], v[24:27]
	v_mfma_f32_16x16x32_bf16 v[16:19], v[176:179], v[200:203], v[16:19]
	v_mfma_f32_16x16x32_bf16 v[8:11], v[168:171], v[208:211], v[8:11]
	v_mfma_f32_16x16x32_bf16 v[0:3], v[176:179], v[208:211], v[0:3]
	v_mfma_f32_16x16x32_bf16 v[56:59], v[172:175], v[188:191], v[56:59]
	v_mfma_f32_16x16x32_bf16 v[48:51], v[180:183], v[188:191], v[48:51]
	v_mfma_f32_16x16x32_bf16 v[40:43], v[172:175], v[196:199], v[40:43]
	v_mfma_f32_16x16x32_bf16 v[32:35], v[180:183], v[196:199], v[32:35]
	v_mfma_f32_16x16x32_bf16 v[24:27], v[172:175], v[204:207], v[24:27]
	v_mfma_f32_16x16x32_bf16 v[16:19], v[180:183], v[204:207], v[16:19]
	v_mfma_f32_16x16x32_bf16 v[8:11], v[172:175], v[212:215], v[8:11]
	v_mfma_f32_16x16x32_bf16 v[0:3], v[180:183], v[212:215], v[0:3]
	s_barrier
	s_add_i32 s66, s66, 2
	s_add_u32 s64, s64, 0x100
	s_addc_u32 s65, s65, 0
	s_cmp_gt_u32 s66, 61
	s_mov_b64 s[48:49], s[4:5]
	s_cbranch_scc0 .LBB0_233
	s_add_u32 s98, s44, 0x80
	s_addc_u32 s99, s45, 0
	s_add_u32 s100, s44, 0x104080
	s_addc_u32 s101, s45, 0
	s_add_i32 m0, s23, 0xc000
	s_nop 0
	global_load_lds_dwordx4 v134, s[100:101]
	s_add_i32 m0, s23, 0xe000
	s_nop 0
	global_load_lds_dwordx4 v130, s[100:101]
	s_mov_b32 m0, s55
	s_nop 0
	global_load_lds_dwordx4 v134, s[98:99]
	s_mov_b32 m0, s56
	s_nop 0
	global_load_lds_dwordx4 v130, s[98:99]
	s_and_b64 vcc, exec, s[42:43]
	s_cbranch_vccz .LBB0_236
	s_barrier

; #define PG8_STAGE(bufoff, gbase, voff) do { _Pragma("unroll") for (int _i = 0; _i < 2; ++_i) \
;         __builtin_amdgcn_global_load_lds((const unsigned*)((const char*)(gbase) + (voff)[_i]), (PG8_LAS unsigned*)(lds + (bufoff) + ldsw + _i * 8192), 16, 0, 0); } while (0)
; #define PG8_LDA(dst, b, h) do { _Pragma("unroll") for (int m = 0; m < 4; ++m) _Pragma("unroll") for (int k = 0; k < 2; ++k) dst[m][k] = *(const PG8_LAS bf16x8*)(lds + PG8_SA(b, h) + aoff + m * 2048 + k * 1024); } while (0)
; #define PG8_LDB(dst, b, h) do { _Pragma("unroll") for (int n = 0; n < 2; ++n) _Pragma("unroll") for (int k = 0; k < 2; ++k) dst[n][k] = *(const PG8_LAS bf16x8*)(lds + PG8_SB(b, h) + boff + n * 2048 + k * 1024); } while (0)
; #define PG8_MMA(ai, bj, At, Bt) do { __builtin_amdgcn_s_setprio(1); _Pragma("unroll") for (int m = 0; m < 4; ++m) _Pragma("unroll") for (int n = 0; n < 2; ++n) _Pragma("unroll") for (int k = 0; k < 2; ++k) \
;         acc[ai][bj][m][n] = __builtin_amdgcn_mfma_f32_16x16x32_bf16(Bt[n][k], At[m][k], acc[ai][bj][m][n], 0, 0, 0); __builtin_amdgcn_s_setprio(0); } while (0)
; #define PG8_WAIT_V(n) asm volatile("s_waitcnt vmcnt(" #n ")" ::: "memory")
; #define PG8_WAIT_L(n) asm volatile("s_waitcnt lgkmcnt(" #n ")" ::: "memory")
; #define PG8_BAR __builtin_amdgcn_s_barrier()
; #define PG8_SCHED __builtin_amdgcn_sched_barrier(0)
; template <class Epi, class Sched, bool ALIGN_EPI = false, bool SP2 = false>
; __device__ __forceinline__ void gemm_phase(PG8_LAS unsigned char* lds, const Gemm g, const Sched& S, const Epi& E, int wid) {
;     ...
;         for (int t = 0; t < nt; t += 2) {
;             const bool last = (t == nt - 2);
;             const char* a1 = cA + (size_t)(t + 1) * kstep;
;             const char* a2 = last ? nA : cA + (size_t)(t + 2) * kstep; const char* b2 = last ? nB : cB + (size_t)(t + 2) * kstep;
;             const char* a3 = a2 + kstep; const char* b3 = b2 + kstep;
;             if (last && has_next) S.a_ready(nxt);
;             if constexpr (SP2) {
;             PG8_LDB(B0, 0, 0); PG8_LDB(B1, 0, 1); PG8_SCHED; PG8_LDA(At, 0, 0); PG8_STAGE(PG8_SA(1, 1), a1 + hstepA, voffA);
;             PG8_WAIT_V(8); PG8_WAIT_L(0); PG8_BAR; PG8_MMA(0, 0, At, B0); PG8_MMA(0, 1, At, B1); PG8_BAR; PG8_SCHED;
.LBB0_426:
	ds_read_b128 v[144:147], v161
	ds_read_b128 v[148:151], v161 offset:1024
	ds_read_b128 v[152:155], v161 offset:2048
	ds_read_b128 v[166:169], v161 offset:3072
	ds_read_b128 v[170:173], v162
	ds_read_b128 v[174:177], v162 offset:1024
	ds_read_b128 v[178:181], v162 offset:2048
	ds_read_b128 v[182:185], v162 offset:3072
	s_add_u32 s4, s46, 0x100
	s_addc_u32 s5, s47, 0
	s_add_u32 s98, s46, 0x80
	s_addc_u32 s99, s47, 0
	s_add_u32 s100, s46, 0x104080
	s_addc_u32 s101, s47, 0
	s_cmp_eq_u32 s64, 60
	s_cselect_b32 s51, s43, s5
	s_cselect_b32 s50, s42, s4
	s_cselect_b32 s49, s45, s63
	s_cselect_b32 s48, s44, s62
	s_add_i32 m0, s23, 0xc000
	ds_read_b128 v[186:189], v163
	ds_read_b128 v[190:193], v163 offset:1024
	ds_read_b128 v[194:197], v163 offset:2048
	ds_read_b128 v[198:201], v163 offset:3072
	ds_read_b128 v[202:205], v163 offset:4096
	ds_read_b128 v[206:209], v163 offset:5120
	ds_read_b128 v[210:213], v163 offset:6144
	ds_read_b128 v[214:217], v163 offset:7168
	global_load_lds_dwordx4 v134, s[100:101]
	s_add_i32 m0, s23, 0xe000
	s_nop 0
	global_load_lds_dwordx4 v130, s[100:101]
	s_mov_b32 m0, s53
	s_nop 0
	global_load_lds_dwordx4 v134, s[98:99]
	s_mov_b32 m0, s54
	s_nop 0
	global_load_lds_dwordx4 v130, s[98:99]
	s_cmp_lg_u32 s64, -2
	s_cbranch_scc1 .Lrx1_0_std
	s_cmp_eq_u32 s52, 1
	s_cbranch_scc1 .Lrx1_0_std
	s_waitcnt vmcnt(24)
	s_branch .Lrx1_0_done

; #define PG8_STAGE(bufoff, gbase, voff) do { _Pragma("unroll") for (int _i = 0; _i < 2; ++_i) \
;         __builtin_amdgcn_global_load_lds((const unsigned*)((const char*)(gbase) + (voff)[_i]), (PG8_LAS unsigned*)(lds + (bufoff) + ldsw + _i * 8192), 16, 0, 0); } while (0)
; #define PG8_STAGE_NT(bufoff, gbase, voff) do { _Pragma("unroll") for (int _i = 0; _i < 2; ++_i) \
;         __builtin_amdgcn_global_load_lds((const unsigned*)((const char*)(gbase) + (voff)[_i]), (PG8_LAS unsigned*)(lds + (bufoff) + ldsw + _i * 8192), 16, 0, PG8_B_AUX); } while (0)
; #define PG8_LDA(dst, b, h) do { _Pragma("unroll") for (int m = 0; m < 4; ++m) _Pragma("unroll") for (int k = 0; k < 2; ++k) dst[m][k] = *(const PG8_LAS bf16x8*)(lds + PG8_SA(b, h) + aoff + m * 2048 + k * 1024); } while (0)
; #define PG8_MMA(ai, bj, At, Bt) do { __builtin_amdgcn_s_setprio(1); _Pragma("unroll") for (int m = 0; m < 4; ++m) _Pragma("unroll") for (int n = 0; n < 2; ++n) _Pragma("unroll") for (int k = 0; k < 2; ++k) \
;         acc[ai][bj][m][n] = __builtin_amdgcn_mfma_f32_16x16x32_bf16(Bt[n][k], At[m][k], acc[ai][bj][m][n], 0, 0, 0); __builtin_amdgcn_s_setprio(0); } while (0)
; #define PG8_WAIT_V(n) asm volatile("s_waitcnt vmcnt(" #n ")" ::: "memory")
; #define PG8_WAIT_L(n) asm volatile("s_waitcnt lgkmcnt(" #n ")" ::: "memory")
; #define PG8_BAR __builtin_amdgcn_s_barrier()
; #define PG8_SCHED __builtin_amdgcn_sched_barrier(0)
; template <class Epi, class Sched, bool ALIGN_EPI = false, bool SP2 = false>
; __device__ __forceinline__ void gemm_phase(PG8_LAS unsigned char* lds, const Gemm g, const Sched& S, const Epi& E, int wid) {
;     ...
;             PG8_WAIT_V(8); PG8_WAIT_L(0); PG8_BAR; PG8_MMA(0, 0, At, B0); PG8_MMA(0, 1, At, B1); PG8_BAR; PG8_SCHED;
;             PG8_LDA(At, 0, 1); PG8_STAGE_NT(PG8_SB(0, 0), b2, voffB); PG8_STAGE_NT(PG8_SB(0, 1), b2 + hstepB, voffB); PG8_STAGE(PG8_SA(0, 0), a2, voffA);
.Lrx1_0_done:
	s_waitcnt lgkmcnt(0)
	s_barrier
	s_waitcnt lgkmcnt(0)
	v_mfma_f32_16x16x32_bf16 v[124:127], v[144:147], v[186:189], v[124:127]
	v_mfma_f32_16x16x32_bf16 v[120:123], v[152:155], v[186:189], v[120:123]
	v_mfma_f32_16x16x32_bf16 v[116:119], v[144:147], v[194:197], v[116:119]
	v_mfma_f32_16x16x32_bf16 v[112:115], v[152:155], v[194:197], v[112:115]
	v_mfma_f32_16x16x32_bf16 v[92:95], v[144:147], v[202:205], v[92:95]
	v_mfma_f32_16x16x32_bf16 v[88:91], v[152:155], v[202:205], v[88:91]
	v_mfma_f32_16x16x32_bf16 v[76:79], v[144:147], v[210:213], v[76:79]
	v_mfma_f32_16x16x32_bf16 v[72:75], v[152:155], v[210:213], v[72:75]
	v_mfma_f32_16x16x32_bf16 v[124:127], v[148:151], v[190:193], v[124:127]
	v_mfma_f32_16x16x32_bf16 v[120:123], v[166:169], v[190:193], v[120:123]
	v_mfma_f32_16x16x32_bf16 v[116:119], v[148:151], v[198:201], v[116:119]
	v_mfma_f32_16x16x32_bf16 v[112:115], v[166:169], v[198:201], v[112:115]
	v_mfma_f32_16x16x32_bf16 v[92:95], v[148:151], v[206:209], v[92:95]
	v_mfma_f32_16x16x32_bf16 v[88:91], v[166:169], v[206:209], v[88:91]
	v_mfma_f32_16x16x32_bf16 v[76:79], v[148:151], v[214:217], v[76:79]
	v_mfma_f32_16x16x32_bf16 v[72:75], v[166:169], v[214:217], v[72:75]
	v_mfma_f32_16x16x32_bf16 v[108:111], v[170:173], v[186:189], v[108:111]
	v_mfma_f32_16x16x32_bf16 v[104:107], v[178:181], v[186:189], v[104:107]
	v_mfma_f32_16x16x32_bf16 v[100:103], v[170:173], v[194:197], v[100:103]
	v_mfma_f32_16x16x32_bf16 v[96:99], v[178:181], v[194:197], v[96:99]
	v_mfma_f32_16x16x32_bf16 v[84:87], v[170:173], v[202:205], v[84:87]
	v_mfma_f32_16x16x32_bf16 v[80:83], v[178:181], v[202:205], v[80:83]
	v_mfma_f32_16x16x32_bf16 v[68:71], v[170:173], v[210:213], v[68:71]
	v_mfma_f32_16x16x32_bf16 v[64:67], v[178:181], v[210:213], v[64:67]
	v_mfma_f32_16x16x32_bf16 v[108:111], v[174:177], v[190:193], v[108:111]
	v_mfma_f32_16x16x32_bf16 v[104:107], v[182:185], v[190:193], v[104:107]
	v_mfma_f32_16x16x32_bf16 v[100:103], v[174:177], v[198:201], v[100:103]
	v_mfma_f32_16x16x32_bf16 v[96:99], v[182:185], v[198:201], v[96:99]
	v_mfma_f32_16x16x32_bf16 v[84:87], v[174:177], v[206:209], v[84:87]
	v_mfma_f32_16x16x32_bf16 v[80:83], v[182:185], v[206:209], v[80:83]
	v_mfma_f32_16x16x32_bf16 v[68:71], v[174:177], v[214:217], v[68:71]
	v_mfma_f32_16x16x32_bf16 v[64:67], v[182:185], v[214:217], v[64:67]
	s_barrier
	s_add_i32 s46, s56, s17
	s_mov_b32 m0, s46
	ds_read_b128 v[186:189], v163 offset:16384
	ds_read_b128 v[190:193], v163 offset:17408
	ds_read_b128 v[194:197], v163 offset:18432
	ds_read_b128 v[198:201], v163 offset:19456
	ds_read_b128 v[202:205], v163 offset:20480
	ds_read_b128 v[206:209], v163 offset:21504
	ds_read_b128 v[210:213], v163 offset:22528
	ds_read_b128 v[214:217], v163 offset:23552
	global_load_lds_dwordx4 v132, s[48:49]
	s_add_i32 m0, s46, 0x2000
	s_add_u32 s46, s48, 0x104000
	s_addc_u32 s47, s49, 0
	s_add_i32 s65, s57, s17
	global_load_lds_dwordx4 v128, s[48:49]
	s_mov_b32 m0, s65
	s_nop 0
	global_load_lds_dwordx4 v132, s[46:47]
	s_add_i32 m0, s65, 0x2000
	s_nop 0
	global_load_lds_dwordx4 v128, s[46:47]
	s_cmp_lg_u32 s64, -2
	s_cbranch_scc1 .Lrx1_1_std
	s_cmp_eq_u32 s52, 1
	s_cbranch_scc1 .Lrx1_1_std
	s_waitcnt vmcnt(24)
	s_branch .Lrx1_1_done

; #define PG8_STAGE(bufoff, gbase, voff) do { _Pragma("unroll") for (int _i = 0; _i < 2; ++_i) \
;         __builtin_amdgcn_global_load_lds((const unsigned*)((const char*)(gbase) + (voff)[_i]), (PG8_LAS unsigned*)(lds + (bufoff) + ldsw + _i * 8192), 16, 0, 0); } while (0)
; #define PG8_LDA(dst, b, h) do { _Pragma("unroll") for (int m = 0; m < 4; ++m) _Pragma("unroll") for (int k = 0; k < 2; ++k) dst[m][k] = *(const PG8_LAS bf16x8*)(lds + PG8_SA(b, h) + aoff + m * 2048 + k * 1024); } while (0)
; #define PG8_LDB(dst, b, h) do { _Pragma("unroll") for (int n = 0; n < 2; ++n) _Pragma("unroll") for (int k = 0; k < 2; ++k) dst[n][k] = *(const PG8_LAS bf16x8*)(lds + PG8_SB(b, h) + boff + n * 2048 + k * 1024); } while (0)
; #define PG8_MMA(ai, bj, At, Bt) do { __builtin_amdgcn_s_setprio(1); _Pragma("unroll") for (int m = 0; m < 4; ++m) _Pragma("unroll") for (int n = 0; n < 2; ++n) _Pragma("unroll") for (int k = 0; k < 2; ++k) \
;         acc[ai][bj][m][n] = __builtin_amdgcn_mfma_f32_16x16x32_bf16(Bt[n][k], At[m][k], acc[ai][bj][m][n], 0, 0, 0); __builtin_amdgcn_s_setprio(0); } while (0)
; #define PG8_WAIT_V(n) asm volatile("s_waitcnt vmcnt(" #n ")" ::: "memory")
; #define PG8_WAIT_L(n) asm volatile("s_waitcnt lgkmcnt(" #n ")" ::: "memory")
; #define PG8_BAR __builtin_amdgcn_s_barrier()
; #define PG8_SCHED __builtin_amdgcn_sched_barrier(0)
; template <class Epi, class Sched, bool ALIGN_EPI = false, bool SP2 = false>
; __device__ __forceinline__ void gemm_phase(PG8_LAS unsigned char* lds, const Gemm g, const Sched& S, const Epi& E, int wid) {
;     ...
;             PG8_WAIT_V(8); PG8_WAIT_L(0); PG8_BAR; PG8_MMA(1, 0, At, B0); PG8_MMA(1, 1, At, B1); PG8_BAR; PG8_SCHED;
;             PG8_LDB(B0, 1, 0); PG8_LDB(B1, 1, 1); PG8_SCHED; PG8_LDA(At, 1, 0); PG8_STAGE(PG8_SA(0, 1), a2 + hstepA, voffA);
.Lrx1_1_done:
	s_waitcnt lgkmcnt(0)
	s_barrier
	s_waitcnt lgkmcnt(0)
	v_mfma_f32_16x16x32_bf16 v[60:63], v[144:147], v[186:189], v[60:63]
	v_mfma_f32_16x16x32_bf16 v[56:59], v[152:155], v[186:189], v[56:59]
	v_mfma_f32_16x16x32_bf16 v[44:47], v[144:147], v[194:197], v[44:47]
	v_mfma_f32_16x16x32_bf16 v[40:43], v[152:155], v[194:197], v[40:43]
	v_mfma_f32_16x16x32_bf16 v[28:31], v[144:147], v[202:205], v[28:31]
	v_mfma_f32_16x16x32_bf16 v[24:27], v[152:155], v[202:205], v[24:27]
	v_mfma_f32_16x16x32_bf16 v[12:15], v[144:147], v[210:213], v[12:15]
	v_mfma_f32_16x16x32_bf16 v[8:11], v[152:155], v[210:213], v[8:11]
	v_mfma_f32_16x16x32_bf16 v[60:63], v[148:151], v[190:193], v[60:63]
	v_mfma_f32_16x16x32_bf16 v[56:59], v[166:169], v[190:193], v[56:59]
	v_mfma_f32_16x16x32_bf16 v[44:47], v[148:151], v[198:201], v[44:47]
	v_mfma_f32_16x16x32_bf16 v[40:43], v[166:169], v[198:201], v[40:43]
	v_mfma_f32_16x16x32_bf16 v[28:31], v[148:151], v[206:209], v[28:31]
	v_mfma_f32_16x16x32_bf16 v[24:27], v[166:169], v[206:209], v[24:27]
	v_mfma_f32_16x16x32_bf16 v[12:15], v[148:151], v[214:217], v[12:15]
	v_mfma_f32_16x16x32_bf16 v[8:11], v[166:169], v[214:217], v[8:11]
	v_mfma_f32_16x16x32_bf16 v[52:55], v[170:173], v[186:189], v[52:55]
	v_mfma_f32_16x16x32_bf16 v[48:51], v[178:181], v[186:189], v[48:51]
	v_mfma_f32_16x16x32_bf16 v[36:39], v[170:173], v[194:197], v[36:39]
	v_mfma_f32_16x16x32_bf16 v[32:35], v[178:181], v[194:197], v[32:35]
	v_mfma_f32_16x16x32_bf16 v[20:23], v[170:173], v[202:205], v[20:23]
	v_mfma_f32_16x16x32_bf16 v[16:19], v[178:181], v[202:205], v[16:19]
	v_mfma_f32_16x16x32_bf16 v[4:7], v[170:173], v[210:213], v[4:7]
	v_mfma_f32_16x16x32_bf16 v[0:3], v[178:181], v[210:213], v[0:3]
	v_mfma_f32_16x16x32_bf16 v[52:55], v[174:177], v[190:193], v[52:55]
	v_mfma_f32_16x16x32_bf16 v[48:51], v[182:185], v[190:193], v[48:51]
	v_mfma_f32_16x16x32_bf16 v[36:39], v[174:177], v[198:201], v[36:39]
	v_mfma_f32_16x16x32_bf16 v[32:35], v[182:185], v[198:201], v[32:35]
	v_mfma_f32_16x16x32_bf16 v[20:23], v[174:177], v[206:209], v[20:23]
	v_mfma_f32_16x16x32_bf16 v[16:19], v[182:185], v[206:209], v[16:19]
	v_mfma_f32_16x16x32_bf16 v[4:7], v[174:177], v[214:217], v[4:7]
	v_mfma_f32_16x16x32_bf16 v[0:3], v[182:185], v[214:217], v[0:3]
	s_barrier
	s_add_i32 s65, 0, 0x18000
	v_add_u32_e32 v165, s65, v159
	s_add_i32 s66, 0, 0x1c000
	ds_read_b128 v[144:147], v165
	ds_read_b128 v[148:151], v165 offset:1024
	ds_read_b128 v[152:155], v165 offset:2048
	ds_read_b128 v[166:169], v165 offset:3072
	v_add_u32_e32 v165, s66, v159
	ds_read_b128 v[170:173], v165
	ds_read_b128 v[174:177], v165 offset:1024
	ds_read_b128 v[178:181], v165 offset:2048
	ds_read_b128 v[182:185], v165 offset:3072
	s_add_u32 s46, s50, 0x104000
	s_addc_u32 s47, s51, 0
	s_mov_b32 m0, s25
	ds_read_b128 v[186:189], v163 offset:32768
	ds_read_b128 v[190:193], v163 offset:33792
	ds_read_b128 v[194:197], v163 offset:34816
	ds_read_b128 v[198:201], v163 offset:35840
	ds_read_b128 v[202:205], v163 offset:36864
	ds_read_b128 v[206:209], v163 offset:37888
	ds_read_b128 v[210:213], v163 offset:38912
	ds_read_b128 v[214:217], v163 offset:39936
	global_load_lds_dwordx4 v134, s[46:47]
	s_mov_b32 m0, s29
	s_nop 0
	global_load_lds_dwordx4 v130, s[46:47]
	s_mov_b32 m0, s23
	s_nop 0
	global_load_lds_dwordx4 v134, s[50:51]
	s_mov_b32 m0, s24
	s_nop 0
	global_load_lds_dwordx4 v130, s[50:51]
	s_cmp_lg_u32 s64, -2
	s_cbranch_scc1 .Lrx1_2_std
	s_cmp_eq_u32 s52, 1
	s_cbranch_scc1 .Lrx1_2_std
	s_waitcnt vmcnt(28)
	s_branch .Lrx1_2_done

; #define PG8_STAGE(bufoff, gbase, voff) do { _Pragma("unroll") for (int _i = 0; _i < 2; ++_i) \
;         __builtin_amdgcn_global_load_lds((const unsigned*)((const char*)(gbase) + (voff)[_i]), (PG8_LAS unsigned*)(lds + (bufoff) + ldsw + _i * 8192), 16, 0, 0); } while (0)
; #define PG8_STAGE_NT(bufoff, gbase, voff) do { _Pragma("unroll") for (int _i = 0; _i < 2; ++_i) \
;         __builtin_amdgcn_global_load_lds((const unsigned*)((const char*)(gbase) + (voff)[_i]), (PG8_LAS unsigned*)(lds + (bufoff) + ldsw + _i * 8192), 16, 0, PG8_B_AUX); } while (0)
; #define PG8_LDA(dst, b, h) do { _Pragma("unroll") for (int m = 0; m < 4; ++m) _Pragma("unroll") for (int k = 0; k < 2; ++k) dst[m][k] = *(const PG8_LAS bf16x8*)(lds + PG8_SA(b, h) + aoff + m * 2048 + k * 1024); } while (0)
; #define PG8_MMA(ai, bj, At, Bt) do { __builtin_amdgcn_s_setprio(1); _Pragma("unroll") for (int m = 0; m < 4; ++m) _Pragma("unroll") for (int n = 0; n < 2; ++n) _Pragma("unroll") for (int k = 0; k < 2; ++k) \
;         acc[ai][bj][m][n] = __builtin_amdgcn_mfma_f32_16x16x32_bf16(Bt[n][k], At[m][k], acc[ai][bj][m][n], 0, 0, 0); __builtin_amdgcn_s_setprio(0); } while (0)
; #define PG8_WAIT_V(n) asm volatile("s_waitcnt vmcnt(" #n ")" ::: "memory")
; #define PG8_WAIT_L(n) asm volatile("s_waitcnt lgkmcnt(" #n ")" ::: "memory")
; #define PG8_BAR __builtin_amdgcn_s_barrier()
; #define PG8_SCHED __builtin_amdgcn_sched_barrier(0)
; template <class Epi, class Sched, bool ALIGN_EPI = false, bool SP2 = false>
; __device__ __forceinline__ void gemm_phase(PG8_LAS unsigned char* lds, const Gemm g, const Sched& S, const Epi& E, int wid) {
;     ...
;             PG8_WAIT_V(8); PG8_WAIT_L(0); PG8_BAR; PG8_MMA(0, 0, At, B0); PG8_MMA(0, 1, At, B1); PG8_BAR; PG8_SCHED;
;             PG8_LDA(At, 1, 1); PG8_STAGE_NT(PG8_SB(1, 0), b3, voffB); PG8_STAGE_NT(PG8_SB(1, 1), b3 + hstepB, voffB); PG8_STAGE(PG8_SA(1, 0), a3, voffA);
;             PG8_WAIT_V(8); PG8_WAIT_L(0); PG8_BAR; PG8_MMA(1, 0, At, B0); PG8_MMA(1, 1, At, B1); PG8_BAR; PG8_SCHED;
.Lrx1_2_done:
	s_waitcnt lgkmcnt(0)
	s_barrier
	s_waitcnt lgkmcnt(0)
	v_mfma_f32_16x16x32_bf16 v[124:127], v[144:147], v[186:189], v[124:127]
	v_mfma_f32_16x16x32_bf16 v[120:123], v[152:155], v[186:189], v[120:123]
	v_mfma_f32_16x16x32_bf16 v[116:119], v[144:147], v[194:197], v[116:119]
	v_mfma_f32_16x16x32_bf16 v[112:115], v[152:155], v[194:197], v[112:115]
	v_mfma_f32_16x16x32_bf16 v[92:95], v[144:147], v[202:205], v[92:95]
	v_mfma_f32_16x16x32_bf16 v[88:91], v[152:155], v[202:205], v[88:91]
	v_mfma_f32_16x16x32_bf16 v[76:79], v[144:147], v[210:213], v[76:79]
	v_mfma_f32_16x16x32_bf16 v[72:75], v[152:155], v[210:213], v[72:75]
	v_mfma_f32_16x16x32_bf16 v[124:127], v[148:151], v[190:193], v[124:127]
	v_mfma_f32_16x16x32_bf16 v[120:123], v[166:169], v[190:193], v[120:123]
	v_mfma_f32_16x16x32_bf16 v[116:119], v[148:151], v[198:201], v[116:119]
	v_mfma_f32_16x16x32_bf16 v[112:115], v[166:169], v[198:201], v[112:115]
	v_mfma_f32_16x16x32_bf16 v[92:95], v[148:151], v[206:209], v[92:95]
	v_mfma_f32_16x16x32_bf16 v[88:91], v[166:169], v[206:209], v[88:91]
	v_mfma_f32_16x16x32_bf16 v[76:79], v[148:151], v[214:217], v[76:79]
	v_mfma_f32_16x16x32_bf16 v[72:75], v[166:169], v[214:217], v[72:75]
	v_mfma_f32_16x16x32_bf16 v[108:111], v[170:173], v[186:189], v[108:111]
	v_mfma_f32_16x16x32_bf16 v[104:107], v[178:181], v[186:189], v[104:107]
	v_mfma_f32_16x16x32_bf16 v[100:103], v[170:173], v[194:197], v[100:103]
	v_mfma_f32_16x16x32_bf16 v[96:99], v[178:181], v[194:197], v[96:99]
	v_mfma_f32_16x16x32_bf16 v[84:87], v[170:173], v[202:205], v[84:87]
	v_mfma_f32_16x16x32_bf16 v[80:83], v[178:181], v[202:205], v[80:83]
	v_mfma_f32_16x16x32_bf16 v[68:71], v[170:173], v[210:213], v[68:71]
	v_mfma_f32_16x16x32_bf16 v[64:67], v[178:181], v[210:213], v[64:67]
	v_mfma_f32_16x16x32_bf16 v[108:111], v[174:177], v[190:193], v[108:111]
	v_mfma_f32_16x16x32_bf16 v[104:107], v[182:185], v[190:193], v[104:107]
	v_mfma_f32_16x16x32_bf16 v[100:103], v[174:177], v[198:201], v[100:103]
	v_mfma_f32_16x16x32_bf16 v[96:99], v[182:185], v[198:201], v[96:99]
	v_mfma_f32_16x16x32_bf16 v[84:87], v[174:177], v[206:209], v[84:87]
	v_mfma_f32_16x16x32_bf16 v[80:83], v[182:185], v[206:209], v[80:83]
	v_mfma_f32_16x16x32_bf16 v[68:71], v[174:177], v[214:217], v[68:71]
	v_mfma_f32_16x16x32_bf16 v[64:67], v[182:185], v[214:217], v[64:67]
	s_barrier
	s_add_i32 s46, s65, s17
	s_mov_b32 m0, s46
	s_add_u32 s98, s48, 0x80
	s_addc_u32 s99, s49, 0
	ds_read_b128 v[186:189], v163 offset:49152
	ds_read_b128 v[190:193], v163 offset:50176
	ds_read_b128 v[194:197], v163 offset:51200
	ds_read_b128 v[198:201], v163 offset:52224
	ds_read_b128 v[202:205], v163 offset:53248
	ds_read_b128 v[206:209], v163 offset:54272
	ds_read_b128 v[210:213], v163 offset:55296
	ds_read_b128 v[214:217], v163 offset:56320
	global_load_lds_dwordx4 v132, s[98:99]
	s_add_i32 m0, s46, 0x2000
	s_add_u32 s46, s48, 0x104080
	s_addc_u32 s47, s49, 0
	s_add_i32 s48, s66, s17
	global_load_lds_dwordx4 v128, s[98:99]
	s_mov_b32 m0, s48
	s_nop 0
	global_load_lds_dwordx4 v132, s[46:47]
	s_add_i32 m0, s48, 0x2000
	s_nop 0
	global_load_lds_dwordx4 v128, s[46:47]
	s_waitcnt vmcnt(4)
	s_waitcnt lgkmcnt(0)
	s_barrier
	s_waitcnt lgkmcnt(0)
	v_mfma_f32_16x16x32_bf16 v[60:63], v[144:147], v[186:189], v[60:63]
	v_mfma_f32_16x16x32_bf16 v[56:59], v[152:155], v[186:189], v[56:59]
	v_mfma_f32_16x16x32_bf16 v[44:47], v[144:147], v[194:197], v[44:47]
	v_mfma_f32_16x16x32_bf16 v[40:43], v[152:155], v[194:197], v[40:43]
	v_mfma_f32_16x16x32_bf16 v[28:31], v[144:147], v[202:205], v[28:31]
	v_mfma_f32_16x16x32_bf16 v[24:27], v[152:155], v[202:205], v[24:27]
	v_mfma_f32_16x16x32_bf16 v[12:15], v[144:147], v[210:213], v[12:15]
	v_mfma_f32_16x16x32_bf16 v[8:11], v[152:155], v[210:213], v[8:11]
	v_mfma_f32_16x16x32_bf16 v[60:63], v[148:151], v[190:193], v[60:63]
	v_mfma_f32_16x16x32_bf16 v[56:59], v[166:169], v[190:193], v[56:59]
	v_mfma_f32_16x16x32_bf16 v[44:47], v[148:151], v[198:201], v[44:47]
	v_mfma_f32_16x16x32_bf16 v[40:43], v[166:169], v[198:201], v[40:43]
	v_mfma_f32_16x16x32_bf16 v[28:31], v[148:151], v[206:209], v[28:31]
	v_mfma_f32_16x16x32_bf16 v[24:27], v[166:169], v[206:209], v[24:27]
	v_mfma_f32_16x16x32_bf16 v[12:15], v[148:151], v[214:217], v[12:15]
	v_mfma_f32_16x16x32_bf16 v[8:11], v[166:169], v[214:217], v[8:11]
	v_mfma_f32_16x16x32_bf16 v[52:55], v[170:173], v[186:189], v[52:55]
	v_mfma_f32_16x16x32_bf16 v[48:51], v[178:181], v[186:189], v[48:51]
	v_mfma_f32_16x16x32_bf16 v[36:39], v[170:173], v[194:197], v[36:39]
	v_mfma_f32_16x16x32_bf16 v[32:35], v[178:181], v[194:197], v[32:35]
	v_mfma_f32_16x16x32_bf16 v[20:23], v[170:173], v[202:205], v[20:23]
	v_mfma_f32_16x16x32_bf16 v[16:19], v[178:181], v[202:205], v[16:19]
	v_mfma_f32_16x16x32_bf16 v[4:7], v[170:173], v[210:213], v[4:7]
	v_mfma_f32_16x16x32_bf16 v[0:3], v[178:181], v[210:213], v[0:3]
	v_mfma_f32_16x16x32_bf16 v[52:55], v[174:177], v[190:193], v[52:55]
	v_mfma_f32_16x16x32_bf16 v[48:51], v[182:185], v[190:193], v[48:51]
	v_mfma_f32_16x16x32_bf16 v[36:39], v[174:177], v[198:201], v[36:39]
	v_mfma_f32_16x16x32_bf16 v[32:35], v[182:185], v[198:201], v[32:35]
	v_mfma_f32_16x16x32_bf16 v[20:23], v[174:177], v[206:209], v[20:23]
	v_mfma_f32_16x16x32_bf16 v[16:19], v[182:185], v[206:209], v[16:19]
	v_mfma_f32_16x16x32_bf16 v[4:7], v[174:177], v[214:217], v[4:7]
	v_mfma_f32_16x16x32_bf16 v[0:3], v[182:185], v[214:217], v[0:3]
	s_barrier
	s_add_i32 s64, s64, 2
	s_add_u32 s62, s62, 0x100
	s_addc_u32 s63, s63, 0
	s_cmp_gt_u32 s64, 61
	s_mov_b64 s[46:47], s[4:5]
	s_cbranch_scc0 .LBB0_426
	s_add_u32 s98, s42, 0x80
	s_addc_u32 s99, s43, 0
	s_add_u32 s100, s42, 0x104080
	s_addc_u32 s101, s43, 0
	s_add_i32 m0, s23, 0xc000
	s_nop 0
	global_load_lds_dwordx4 v134, s[100:101]
	s_add_i32 m0, s23, 0xe000
	s_nop 0
	global_load_lds_dwordx4 v130, s[100:101]
	s_mov_b32 m0, s53
	s_nop 0
	global_load_lds_dwordx4 v134, s[98:99]
	s_mov_b32 m0, s54
	s_nop 0
	global_load_lds_dwordx4 v130, s[98:99]
	s_and_b64 vcc, exec, s[40:41]
	s_cbranch_vccz .LBB0_429
	s_barrier

; #define PG8_STAGE(bufoff, gbase, voff) do { _Pragma("unroll") for (int _i = 0; _i < 2; ++_i) \
;         __builtin_amdgcn_global_load_lds((const unsigned*)((const char*)(gbase) + (voff)[_i]), (PG8_LAS unsigned*)(lds + (bufoff) + ldsw + _i * 8192), 16, 0, 0); } while (0)
; #define PG8_LDA(dst, b, h) do { _Pragma("unroll") for (int m = 0; m < 4; ++m) _Pragma("unroll") for (int k = 0; k < 2; ++k) dst[m][k] = *(const PG8_LAS bf16x8*)(lds + PG8_SA(b, h) + aoff + m * 2048 + k * 1024); } while (0)
; #define PG8_LDB(dst, b, h) do { _Pragma("unroll") for (int n = 0; n < 2; ++n) _Pragma("unroll") for (int k = 0; k < 2; ++k) dst[n][k] = *(const PG8_LAS bf16x8*)(lds + PG8_SB(b, h) + boff + n * 2048 + k * 1024); } while (0)
; #define PG8_MMA(ai, bj, At, Bt) do { __builtin_amdgcn_s_setprio(1); _Pragma("unroll") for (int m = 0; m < 4; ++m) _Pragma("unroll") for (int n = 0; n < 2; ++n) _Pragma("unroll") for (int k = 0; k < 2; ++k) \
;         acc[ai][bj][m][n] = __builtin_amdgcn_mfma_f32_16x16x32_bf16(Bt[n][k], At[m][k], acc[ai][bj][m][n], 0, 0, 0); __builtin_amdgcn_s_setprio(0); } while (0)
; #define PG8_WAIT_V(n) asm volatile("s_waitcnt vmcnt(" #n ")" ::: "memory")
; #define PG8_WAIT_L(n) asm volatile("s_waitcnt lgkmcnt(" #n ")" ::: "memory")
; #define PG8_BAR __builtin_amdgcn_s_barrier()
; #define PG8_SCHED __builtin_amdgcn_sched_barrier(0)
; template <class Epi, class Sched, bool ALIGN_EPI = false, bool SP2 = false>
; __device__ __forceinline__ void gemm_phase(PG8_LAS unsigned char* lds, const Gemm g, const Sched& S, const Epi& E, int wid) {
;     ...
;         for (int t = 0; t < nt; t += 2) {
;             const bool last = (t == nt - 2);
;             const char* a1 = cA + (size_t)(t + 1) * kstep;
;             const char* a2 = last ? nA : cA + (size_t)(t + 2) * kstep; const char* b2 = last ? nB : cB + (size_t)(t + 2) * kstep;
;             const char* a3 = a2 + kstep; const char* b3 = b2 + kstep;
;             if (last && has_next) S.a_ready(nxt);
;             if constexpr (SP2) {
;             PG8_LDB(B0, 0, 0); PG8_LDB(B1, 0, 1); PG8_SCHED; PG8_LDA(At, 0, 0); PG8_STAGE(PG8_SA(1, 1), a1 + hstepA, voffA);
;             PG8_WAIT_V(8); PG8_WAIT_L(0); PG8_BAR; PG8_MMA(0, 0, At, B0); PG8_MMA(0, 1, At, B1); PG8_BAR; PG8_SCHED;
.LBB0_1133:
	ds_read_b128 v[144:147], v155
	ds_read_b128 v[148:151], v155 offset:1024
	ds_read_b128 v[160:163], v155 offset:2048
	ds_read_b128 v[164:167], v155 offset:3072
	ds_read_b128 v[168:171], v156
	ds_read_b128 v[172:175], v156 offset:1024
	ds_read_b128 v[176:179], v156 offset:2048
	ds_read_b128 v[180:183], v156 offset:3072
	s_add_u32 s4, s46, 0x100
	s_addc_u32 s5, s47, 0
	s_add_u32 s98, s46, 0x80
	s_addc_u32 s99, s47, 0
	s_add_u32 s100, s46, 0x104080
	s_addc_u32 s101, s47, 0
	s_cmp_eq_u32 s63, 60
	s_cselect_b32 s51, s43, s5
	s_cselect_b32 s50, s42, s4
	s_cselect_b32 s49, s45, s62
	s_cselect_b32 s48, s44, s61
	s_add_i32 m0, s22, 0xc000
	ds_read_b128 v[184:187], v157
	ds_read_b128 v[188:191], v157 offset:1024
	ds_read_b128 v[192:195], v157 offset:2048
	ds_read_b128 v[196:199], v157 offset:3072
	ds_read_b128 v[200:203], v157 offset:4096
	ds_read_b128 v[204:207], v157 offset:5120
	ds_read_b128 v[208:211], v157 offset:6144
	ds_read_b128 v[212:215], v157 offset:7168
	global_load_lds_dwordx4 v134, s[100:101]
	s_add_i32 m0, s22, 0xe000
	s_nop 0
	global_load_lds_dwordx4 v130, s[100:101]
	s_mov_b32 m0, s52
	s_nop 0
	global_load_lds_dwordx4 v134, s[98:99]
	s_mov_b32 m0, s53
	s_nop 0
	global_load_lds_dwordx4 v130, s[98:99]
	s_cmp_lg_u32 s63, -2
	s_cbranch_scc1 .Lrx2_0_std
	s_cmp_eq_u32 s29, 1
	s_cbranch_scc1 .Lrx2_0_std
	s_waitcnt vmcnt(16)
	s_branch .Lrx2_0_done

; #define PG8_STAGE(bufoff, gbase, voff) do { _Pragma("unroll") for (int _i = 0; _i < 2; ++_i) \
;         __builtin_amdgcn_global_load_lds((const unsigned*)((const char*)(gbase) + (voff)[_i]), (PG8_LAS unsigned*)(lds + (bufoff) + ldsw + _i * 8192), 16, 0, 0); } while (0)
; #define PG8_STAGE_NT(bufoff, gbase, voff) do { _Pragma("unroll") for (int _i = 0; _i < 2; ++_i) \
;         __builtin_amdgcn_global_load_lds((const unsigned*)((const char*)(gbase) + (voff)[_i]), (PG8_LAS unsigned*)(lds + (bufoff) + ldsw + _i * 8192), 16, 0, PG8_B_AUX); } while (0)
; #define PG8_LDA(dst, b, h) do { _Pragma("unroll") for (int m = 0; m < 4; ++m) _Pragma("unroll") for (int k = 0; k < 2; ++k) dst[m][k] = *(const PG8_LAS bf16x8*)(lds + PG8_SA(b, h) + aoff + m * 2048 + k * 1024); } while (0)
; #define PG8_MMA(ai, bj, At, Bt) do { __builtin_amdgcn_s_setprio(1); _Pragma("unroll") for (int m = 0; m < 4; ++m) _Pragma("unroll") for (int n = 0; n < 2; ++n) _Pragma("unroll") for (int k = 0; k < 2; ++k) \
;         acc[ai][bj][m][n] = __builtin_amdgcn_mfma_f32_16x16x32_bf16(Bt[n][k], At[m][k], acc[ai][bj][m][n], 0, 0, 0); __builtin_amdgcn_s_setprio(0); } while (0)
; #define PG8_WAIT_V(n) asm volatile("s_waitcnt vmcnt(" #n ")" ::: "memory")
; #define PG8_WAIT_L(n) asm volatile("s_waitcnt lgkmcnt(" #n ")" ::: "memory")
; #define PG8_BAR __builtin_amdgcn_s_barrier()
; #define PG8_SCHED __builtin_amdgcn_sched_barrier(0)
; template <class Epi, class Sched, bool ALIGN_EPI = false, bool SP2 = false>
; __device__ __forceinline__ void gemm_phase(PG8_LAS unsigned char* lds, const Gemm g, const Sched& S, const Epi& E, int wid) {
;     ...
;             PG8_WAIT_V(8); PG8_WAIT_L(0); PG8_BAR; PG8_MMA(0, 0, At, B0); PG8_MMA(0, 1, At, B1); PG8_BAR; PG8_SCHED;
;             PG8_LDA(At, 0, 1); PG8_STAGE_NT(PG8_SB(0, 0), b2, voffB); PG8_STAGE_NT(PG8_SB(0, 1), b2 + hstepB, voffB); PG8_STAGE(PG8_SA(0, 0), a2, voffA);
.Lrx2_0_done:
	s_waitcnt lgkmcnt(0)
	s_barrier
	s_waitcnt lgkmcnt(0)
	v_mfma_f32_16x16x32_bf16 v[112:115], v[144:147], v[184:187], v[112:115]
	v_mfma_f32_16x16x32_bf16 v[108:111], v[160:163], v[184:187], v[108:111]
	v_mfma_f32_16x16x32_bf16 v[104:107], v[144:147], v[192:195], v[104:107]
	v_mfma_f32_16x16x32_bf16 v[100:103], v[160:163], v[192:195], v[100:103]
	v_mfma_f32_16x16x32_bf16 v[92:95], v[144:147], v[200:203], v[92:95]
	v_mfma_f32_16x16x32_bf16 v[84:87], v[160:163], v[200:203], v[84:87]
	v_mfma_f32_16x16x32_bf16 v[76:79], v[144:147], v[208:211], v[76:79]
	v_mfma_f32_16x16x32_bf16 v[68:71], v[160:163], v[208:211], v[68:71]
	v_mfma_f32_16x16x32_bf16 v[112:115], v[148:151], v[188:191], v[112:115]
	v_mfma_f32_16x16x32_bf16 v[108:111], v[164:167], v[188:191], v[108:111]
	v_mfma_f32_16x16x32_bf16 v[104:107], v[148:151], v[196:199], v[104:107]
	v_mfma_f32_16x16x32_bf16 v[100:103], v[164:167], v[196:199], v[100:103]
	v_mfma_f32_16x16x32_bf16 v[92:95], v[148:151], v[204:207], v[92:95]
	v_mfma_f32_16x16x32_bf16 v[84:87], v[164:167], v[204:207], v[84:87]
	v_mfma_f32_16x16x32_bf16 v[76:79], v[148:151], v[212:215], v[76:79]
	v_mfma_f32_16x16x32_bf16 v[68:71], v[164:167], v[212:215], v[68:71]
	v_mfma_f32_16x16x32_bf16 v[124:127], v[168:171], v[184:187], v[124:127]
	v_mfma_f32_16x16x32_bf16 v[120:123], v[176:179], v[184:187], v[120:123]
	v_mfma_f32_16x16x32_bf16 v[116:119], v[168:171], v[192:195], v[116:119]
	v_mfma_f32_16x16x32_bf16 v[96:99], v[176:179], v[192:195], v[96:99]
	v_mfma_f32_16x16x32_bf16 v[88:91], v[168:171], v[200:203], v[88:91]
	v_mfma_f32_16x16x32_bf16 v[80:83], v[176:179], v[200:203], v[80:83]
	v_mfma_f32_16x16x32_bf16 v[72:75], v[168:171], v[208:211], v[72:75]
	v_mfma_f32_16x16x32_bf16 v[64:67], v[176:179], v[208:211], v[64:67]
	v_mfma_f32_16x16x32_bf16 v[124:127], v[172:175], v[188:191], v[124:127]
	v_mfma_f32_16x16x32_bf16 v[120:123], v[180:183], v[188:191], v[120:123]
	v_mfma_f32_16x16x32_bf16 v[116:119], v[172:175], v[196:199], v[116:119]
	v_mfma_f32_16x16x32_bf16 v[96:99], v[180:183], v[196:199], v[96:99]
	v_mfma_f32_16x16x32_bf16 v[88:91], v[172:175], v[204:207], v[88:91]
	v_mfma_f32_16x16x32_bf16 v[80:83], v[180:183], v[204:207], v[80:83]
	v_mfma_f32_16x16x32_bf16 v[72:75], v[172:175], v[212:215], v[72:75]
	v_mfma_f32_16x16x32_bf16 v[64:67], v[180:183], v[212:215], v[64:67]
	s_barrier
	s_add_i32 s46, s55, s9
	s_mov_b32 m0, s46
	ds_read_b128 v[184:187], v157 offset:16384
	ds_read_b128 v[188:191], v157 offset:17408
	ds_read_b128 v[192:195], v157 offset:18432
	ds_read_b128 v[196:199], v157 offset:19456
	ds_read_b128 v[200:203], v157 offset:20480
	ds_read_b128 v[204:207], v157 offset:21504
	ds_read_b128 v[208:211], v157 offset:22528
	ds_read_b128 v[212:215], v157 offset:23552
	global_load_lds_dwordx4 v132, s[48:49]
	s_add_i32 m0, s46, 0x2000
	s_add_u32 s46, s48, 0x104000
	s_addc_u32 s47, s49, 0
	s_add_i32 s64, s56, s9
	global_load_lds_dwordx4 v128, s[48:49]
	s_mov_b32 m0, s64
	s_nop 0
	global_load_lds_dwordx4 v132, s[46:47]
	s_add_i32 m0, s64, 0x2000
	s_nop 0
	global_load_lds_dwordx4 v128, s[46:47]
	s_cmp_lg_u32 s63, -2
	s_cbranch_scc1 .Lrx2_1_std
	s_cmp_eq_u32 s29, 1
	s_cbranch_scc1 .Lrx2_1_std
	s_waitcnt vmcnt(16)
	s_branch .Lrx2_1_done

; #define PG8_STAGE(bufoff, gbase, voff) do { _Pragma("unroll") for (int _i = 0; _i < 2; ++_i) \
;         __builtin_amdgcn_global_load_lds((const unsigned*)((const char*)(gbase) + (voff)[_i]), (PG8_LAS unsigned*)(lds + (bufoff) + ldsw + _i * 8192), 16, 0, 0); } while (0)
; #define PG8_LDA(dst, b, h) do { _Pragma("unroll") for (int m = 0; m < 4; ++m) _Pragma("unroll") for (int k = 0; k < 2; ++k) dst[m][k] = *(const PG8_LAS bf16x8*)(lds + PG8_SA(b, h) + aoff + m * 2048 + k * 1024); } while (0)
; #define PG8_LDB(dst, b, h) do { _Pragma("unroll") for (int n = 0; n < 2; ++n) _Pragma("unroll") for (int k = 0; k < 2; ++k) dst[n][k] = *(const PG8_LAS bf16x8*)(lds + PG8_SB(b, h) + boff + n * 2048 + k * 1024); } while (0)
; #define PG8_MMA(ai, bj, At, Bt) do { __builtin_amdgcn_s_setprio(1); _Pragma("unroll") for (int m = 0; m < 4; ++m) _Pragma("unroll") for (int n = 0; n < 2; ++n) _Pragma("unroll") for (int k = 0; k < 2; ++k) \
;         acc[ai][bj][m][n] = __builtin_amdgcn_mfma_f32_16x16x32_bf16(Bt[n][k], At[m][k], acc[ai][bj][m][n], 0, 0, 0); __builtin_amdgcn_s_setprio(0); } while (0)
; #define PG8_WAIT_V(n) asm volatile("s_waitcnt vmcnt(" #n ")" ::: "memory")
; #define PG8_WAIT_L(n) asm volatile("s_waitcnt lgkmcnt(" #n ")" ::: "memory")
; #define PG8_BAR __builtin_amdgcn_s_barrier()
; #define PG8_SCHED __builtin_amdgcn_sched_barrier(0)
; template <class Epi, class Sched, bool ALIGN_EPI = false, bool SP2 = false>
; __device__ __forceinline__ void gemm_phase(PG8_LAS unsigned char* lds, const Gemm g, const Sched& S, const Epi& E, int wid) {
;     ...
;             PG8_WAIT_V(8); PG8_WAIT_L(0); PG8_BAR; PG8_MMA(1, 0, At, B0); PG8_MMA(1, 1, At, B1); PG8_BAR; PG8_SCHED;
;             PG8_LDB(B0, 1, 0); PG8_LDB(B1, 1, 1); PG8_SCHED; PG8_LDA(At, 1, 0); PG8_STAGE(PG8_SA(0, 1), a2 + hstepA, voffA);
.Lrx2_1_done:
	s_waitcnt lgkmcnt(0)
	s_barrier
	s_waitcnt lgkmcnt(0)
	v_mfma_f32_16x16x32_bf16 v[60:63], v[144:147], v[184:187], v[60:63]
	v_mfma_f32_16x16x32_bf16 v[52:55], v[160:163], v[184:187], v[52:55]
	v_mfma_f32_16x16x32_bf16 v[44:47], v[144:147], v[192:195], v[44:47]
	v_mfma_f32_16x16x32_bf16 v[36:39], v[160:163], v[192:195], v[36:39]
	v_mfma_f32_16x16x32_bf16 v[28:31], v[144:147], v[200:203], v[28:31]
	v_mfma_f32_16x16x32_bf16 v[20:23], v[160:163], v[200:203], v[20:23]
	v_mfma_f32_16x16x32_bf16 v[12:15], v[144:147], v[208:211], v[12:15]
	v_mfma_f32_16x16x32_bf16 v[4:7], v[160:163], v[208:211], v[4:7]
	v_mfma_f32_16x16x32_bf16 v[60:63], v[148:151], v[188:191], v[60:63]
	v_mfma_f32_16x16x32_bf16 v[52:55], v[164:167], v[188:191], v[52:55]
	v_mfma_f32_16x16x32_bf16 v[44:47], v[148:151], v[196:199], v[44:47]
	v_mfma_f32_16x16x32_bf16 v[36:39], v[164:167], v[196:199], v[36:39]
	v_mfma_f32_16x16x32_bf16 v[28:31], v[148:151], v[204:207], v[28:31]
	v_mfma_f32_16x16x32_bf16 v[20:23], v[164:167], v[204:207], v[20:23]
	v_mfma_f32_16x16x32_bf16 v[12:15], v[148:151], v[212:215], v[12:15]
	v_mfma_f32_16x16x32_bf16 v[4:7], v[164:167], v[212:215], v[4:7]
	v_mfma_f32_16x16x32_bf16 v[56:59], v[168:171], v[184:187], v[56:59]
	v_mfma_f32_16x16x32_bf16 v[48:51], v[176:179], v[184:187], v[48:51]
	v_mfma_f32_16x16x32_bf16 v[40:43], v[168:171], v[192:195], v[40:43]
	v_mfma_f32_16x16x32_bf16 v[32:35], v[176:179], v[192:195], v[32:35]
	v_mfma_f32_16x16x32_bf16 v[24:27], v[168:171], v[200:203], v[24:27]
	v_mfma_f32_16x16x32_bf16 v[16:19], v[176:179], v[200:203], v[16:19]
	v_mfma_f32_16x16x32_bf16 v[8:11], v[168:171], v[208:211], v[8:11]
	v_mfma_f32_16x16x32_bf16 v[0:3], v[176:179], v[208:211], v[0:3]
	v_mfma_f32_16x16x32_bf16 v[56:59], v[172:175], v[188:191], v[56:59]
	v_mfma_f32_16x16x32_bf16 v[48:51], v[180:183], v[188:191], v[48:51]
	v_mfma_f32_16x16x32_bf16 v[40:43], v[172:175], v[196:199], v[40:43]
	v_mfma_f32_16x16x32_bf16 v[32:35], v[180:183], v[196:199], v[32:35]
	v_mfma_f32_16x16x32_bf16 v[24:27], v[172:175], v[204:207], v[24:27]
	v_mfma_f32_16x16x32_bf16 v[16:19], v[180:183], v[204:207], v[16:19]
	v_mfma_f32_16x16x32_bf16 v[8:11], v[172:175], v[212:215], v[8:11]
	v_mfma_f32_16x16x32_bf16 v[0:3], v[180:183], v[212:215], v[0:3]
	s_barrier
	s_add_i32 s64, 0, 0x18000
	v_add_u32_e32 v159, s64, v153
	s_add_i32 s65, 0, 0x1c000
	ds_read_b128 v[144:147], v159
	ds_read_b128 v[148:151], v159 offset:1024
	ds_read_b128 v[160:163], v159 offset:2048
	ds_read_b128 v[164:167], v159 offset:3072
	v_add_u32_e32 v159, s65, v153
	ds_read_b128 v[168:171], v159
	ds_read_b128 v[172:175], v159 offset:1024
	ds_read_b128 v[176:179], v159 offset:2048
	ds_read_b128 v[180:183], v159 offset:3072
	s_add_u32 s46, s50, 0x104000
	s_addc_u32 s47, s51, 0
	s_mov_b32 m0, s24
	ds_read_b128 v[184:187], v157 offset:32768
	ds_read_b128 v[188:191], v157 offset:33792
	ds_read_b128 v[192:195], v157 offset:34816
	ds_read_b128 v[196:199], v157 offset:35840
	ds_read_b128 v[200:203], v157 offset:36864
	ds_read_b128 v[204:207], v157 offset:37888
	ds_read_b128 v[208:211], v157 offset:38912
	ds_read_b128 v[212:215], v157 offset:39936
	global_load_lds_dwordx4 v134, s[46:47]
	s_mov_b32 m0, s25
	s_nop 0
	global_load_lds_dwordx4 v130, s[46:47]
	s_mov_b32 m0, s22
	s_nop 0
	global_load_lds_dwordx4 v134, s[50:51]
	s_mov_b32 m0, s23
	s_nop 0
	global_load_lds_dwordx4 v130, s[50:51]
	s_cmp_lg_u32 s63, -2
	s_cbranch_scc1 .Lrx2_2_std
	s_cmp_eq_u32 s29, 1
	s_cbranch_scc1 .Lrx2_2_std
	s_waitcnt vmcnt(20)
	s_branch .Lrx2_2_done

; #define PG8_STAGE(bufoff, gbase, voff) do { _Pragma("unroll") for (int _i = 0; _i < 2; ++_i) \
;         __builtin_amdgcn_global_load_lds((const unsigned*)((const char*)(gbase) + (voff)[_i]), (PG8_LAS unsigned*)(lds + (bufoff) + ldsw + _i * 8192), 16, 0, 0); } while (0)
; #define PG8_STAGE_NT(bufoff, gbase, voff) do { _Pragma("unroll") for (int _i = 0; _i < 2; ++_i) \
;         __builtin_amdgcn_global_load_lds((const unsigned*)((const char*)(gbase) + (voff)[_i]), (PG8_LAS unsigned*)(lds + (bufoff) + ldsw + _i * 8192), 16, 0, PG8_B_AUX); } while (0)
; #define PG8_LDA(dst, b, h) do { _Pragma("unroll") for (int m = 0; m < 4; ++m) _Pragma("unroll") for (int k = 0; k < 2; ++k) dst[m][k] = *(const PG8_LAS bf16x8*)(lds + PG8_SA(b, h) + aoff + m * 2048 + k * 1024); } while (0)
; #define PG8_MMA(ai, bj, At, Bt) do { __builtin_amdgcn_s_setprio(1); _Pragma("unroll") for (int m = 0; m < 4; ++m) _Pragma("unroll") for (int n = 0; n < 2; ++n) _Pragma("unroll") for (int k = 0; k < 2; ++k) \
;         acc[ai][bj][m][n] = __builtin_amdgcn_mfma_f32_16x16x32_bf16(Bt[n][k], At[m][k], acc[ai][bj][m][n], 0, 0, 0); __builtin_amdgcn_s_setprio(0); } while (0)
; #define PG8_WAIT_V(n) asm volatile("s_waitcnt vmcnt(" #n ")" ::: "memory")
; #define PG8_WAIT_L(n) asm volatile("s_waitcnt lgkmcnt(" #n ")" ::: "memory")
; #define PG8_BAR __builtin_amdgcn_s_barrier()
; #define PG8_SCHED __builtin_amdgcn_sched_barrier(0)
; template <class Epi, class Sched, bool ALIGN_EPI = false, bool SP2 = false>
; __device__ __forceinline__ void gemm_phase(PG8_LAS unsigned char* lds, const Gemm g, const Sched& S, const Epi& E, int wid) {
;     ...
;             PG8_WAIT_V(8); PG8_WAIT_L(0); PG8_BAR; PG8_MMA(0, 0, At, B0); PG8_MMA(0, 1, At, B1); PG8_BAR; PG8_SCHED;
;             PG8_LDA(At, 1, 1); PG8_STAGE_NT(PG8_SB(1, 0), b3, voffB); PG8_STAGE_NT(PG8_SB(1, 1), b3 + hstepB, voffB); PG8_STAGE(PG8_SA(1, 0), a3, voffA);
;             PG8_WAIT_V(8); PG8_WAIT_L(0); PG8_BAR; PG8_MMA(1, 0, At, B0); PG8_MMA(1, 1, At, B1); PG8_BAR; PG8_SCHED;
.Lrx2_2_done:
	s_waitcnt lgkmcnt(0)
	s_barrier
	s_waitcnt lgkmcnt(0)
	v_mfma_f32_16x16x32_bf16 v[112:115], v[144:147], v[184:187], v[112:115]
	v_mfma_f32_16x16x32_bf16 v[108:111], v[160:163], v[184:187], v[108:111]
	v_mfma_f32_16x16x32_bf16 v[104:107], v[144:147], v[192:195], v[104:107]
	v_mfma_f32_16x16x32_bf16 v[100:103], v[160:163], v[192:195], v[100:103]
	v_mfma_f32_16x16x32_bf16 v[92:95], v[144:147], v[200:203], v[92:95]
	v_mfma_f32_16x16x32_bf16 v[84:87], v[160:163], v[200:203], v[84:87]
	v_mfma_f32_16x16x32_bf16 v[76:79], v[144:147], v[208:211], v[76:79]
	v_mfma_f32_16x16x32_bf16 v[68:71], v[160:163], v[208:211], v[68:71]
	v_mfma_f32_16x16x32_bf16 v[112:115], v[148:151], v[188:191], v[112:115]
	v_mfma_f32_16x16x32_bf16 v[108:111], v[164:167], v[188:191], v[108:111]
	v_mfma_f32_16x16x32_bf16 v[104:107], v[148:151], v[196:199], v[104:107]
	v_mfma_f32_16x16x32_bf16 v[100:103], v[164:167], v[196:199], v[100:103]
	v_mfma_f32_16x16x32_bf16 v[92:95], v[148:151], v[204:207], v[92:95]
	v_mfma_f32_16x16x32_bf16 v[84:87], v[164:167], v[204:207], v[84:87]
	v_mfma_f32_16x16x32_bf16 v[76:79], v[148:151], v[212:215], v[76:79]
	v_mfma_f32_16x16x32_bf16 v[68:71], v[164:167], v[212:215], v[68:71]
	v_mfma_f32_16x16x32_bf16 v[124:127], v[168:171], v[184:187], v[124:127]
	v_mfma_f32_16x16x32_bf16 v[120:123], v[176:179], v[184:187], v[120:123]
	v_mfma_f32_16x16x32_bf16 v[116:119], v[168:171], v[192:195], v[116:119]
	v_mfma_f32_16x16x32_bf16 v[96:99], v[176:179], v[192:195], v[96:99]
	v_mfma_f32_16x16x32_bf16 v[88:91], v[168:171], v[200:203], v[88:91]
	v_mfma_f32_16x16x32_bf16 v[80:83], v[176:179], v[200:203], v[80:83]
	v_mfma_f32_16x16x32_bf16 v[72:75], v[168:171], v[208:211], v[72:75]
	v_mfma_f32_16x16x32_bf16 v[64:67], v[176:179], v[208:211], v[64:67]
	v_mfma_f32_16x16x32_bf16 v[124:127], v[172:175], v[188:191], v[124:127]
	v_mfma_f32_16x16x32_bf16 v[120:123], v[180:183], v[188:191], v[120:123]
	v_mfma_f32_16x16x32_bf16 v[116:119], v[172:175], v[196:199], v[116:119]
	v_mfma_f32_16x16x32_bf16 v[96:99], v[180:183], v[196:199], v[96:99]
	v_mfma_f32_16x16x32_bf16 v[88:91], v[172:175], v[204:207], v[88:91]
	v_mfma_f32_16x16x32_bf16 v[80:83], v[180:183], v[204:207], v[80:83]
	v_mfma_f32_16x16x32_bf16 v[72:75], v[172:175], v[212:215], v[72:75]
	v_mfma_f32_16x16x32_bf16 v[64:67], v[180:183], v[212:215], v[64:67]
	s_barrier
	s_add_i32 s46, s64, s9
	s_mov_b32 m0, s46
	s_add_u32 s98, s48, 0x80
	s_addc_u32 s99, s49, 0
	ds_read_b128 v[184:187], v157 offset:49152
	ds_read_b128 v[188:191], v157 offset:50176
	ds_read_b128 v[192:195], v157 offset:51200
	ds_read_b128 v[196:199], v157 offset:52224
	ds_read_b128 v[200:203], v157 offset:53248
	ds_read_b128 v[204:207], v157 offset:54272
	ds_read_b128 v[208:211], v157 offset:55296
	ds_read_b128 v[212:215], v157 offset:56320
	global_load_lds_dwordx4 v132, s[98:99]
	s_add_i32 m0, s46, 0x2000
	s_add_u32 s46, s48, 0x104080
	s_addc_u32 s47, s49, 0
	s_add_i32 s48, s65, s9
	global_load_lds_dwordx4 v128, s[98:99]
	s_mov_b32 m0, s48
	s_nop 0
	global_load_lds_dwordx4 v132, s[46:47]
	s_add_i32 m0, s48, 0x2000
	s_nop 0
	global_load_lds_dwordx4 v128, s[46:47]
	s_waitcnt vmcnt(4)
	s_waitcnt lgkmcnt(0)
	s_barrier
	s_waitcnt lgkmcnt(0)
	v_mfma_f32_16x16x32_bf16 v[60:63], v[144:147], v[184:187], v[60:63]
	v_mfma_f32_16x16x32_bf16 v[52:55], v[160:163], v[184:187], v[52:55]
	v_mfma_f32_16x16x32_bf16 v[44:47], v[144:147], v[192:195], v[44:47]
	v_mfma_f32_16x16x32_bf16 v[36:39], v[160:163], v[192:195], v[36:39]
	v_mfma_f32_16x16x32_bf16 v[28:31], v[144:147], v[200:203], v[28:31]
	v_mfma_f32_16x16x32_bf16 v[20:23], v[160:163], v[200:203], v[20:23]
	v_mfma_f32_16x16x32_bf16 v[12:15], v[144:147], v[208:211], v[12:15]
	v_mfma_f32_16x16x32_bf16 v[4:7], v[160:163], v[208:211], v[4:7]
	v_mfma_f32_16x16x32_bf16 v[60:63], v[148:151], v[188:191], v[60:63]
	v_mfma_f32_16x16x32_bf16 v[52:55], v[164:167], v[188:191], v[52:55]
	v_mfma_f32_16x16x32_bf16 v[44:47], v[148:151], v[196:199], v[44:47]
	v_mfma_f32_16x16x32_bf16 v[36:39], v[164:167], v[196:199], v[36:39]
	v_mfma_f32_16x16x32_bf16 v[28:31], v[148:151], v[204:207], v[28:31]
	v_mfma_f32_16x16x32_bf16 v[20:23], v[164:167], v[204:207], v[20:23]
	v_mfma_f32_16x16x32_bf16 v[12:15], v[148:151], v[212:215], v[12:15]
	v_mfma_f32_16x16x32_bf16 v[4:7], v[164:167], v[212:215], v[4:7]
	v_mfma_f32_16x16x32_bf16 v[56:59], v[168:171], v[184:187], v[56:59]
	v_mfma_f32_16x16x32_bf16 v[48:51], v[176:179], v[184:187], v[48:51]
	v_mfma_f32_16x16x32_bf16 v[40:43], v[168:171], v[192:195], v[40:43]
	v_mfma_f32_16x16x32_bf16 v[32:35], v[176:179], v[192:195], v[32:35]
	v_mfma_f32_16x16x32_bf16 v[24:27], v[168:171], v[200:203], v[24:27]
	v_mfma_f32_16x16x32_bf16 v[16:19], v[176:179], v[200:203], v[16:19]
	v_mfma_f32_16x16x32_bf16 v[8:11], v[168:171], v[208:211], v[8:11]
	v_mfma_f32_16x16x32_bf16 v[0:3], v[176:179], v[208:211], v[0:3]
	v_mfma_f32_16x16x32_bf16 v[56:59], v[172:175], v[188:191], v[56:59]
	v_mfma_f32_16x16x32_bf16 v[48:51], v[180:183], v[188:191], v[48:51]
	v_mfma_f32_16x16x32_bf16 v[40:43], v[172:175], v[196:199], v[40:43]
	v_mfma_f32_16x16x32_bf16 v[32:35], v[180:183], v[196:199], v[32:35]
	v_mfma_f32_16x16x32_bf16 v[24:27], v[172:175], v[204:207], v[24:27]
	v_mfma_f32_16x16x32_bf16 v[16:19], v[180:183], v[204:207], v[16:19]
	v_mfma_f32_16x16x32_bf16 v[8:11], v[172:175], v[212:215], v[8:11]
	v_mfma_f32_16x16x32_bf16 v[0:3], v[180:183], v[212:215], v[0:3]
	s_barrier
	s_add_i32 s63, s63, 2
	s_add_u32 s61, s61, 0x100
	s_addc_u32 s62, s62, 0
	s_cmp_gt_u32 s63, 61
	s_mov_b64 s[46:47], s[4:5]
	s_cbranch_scc0 .LBB0_1133
	s_add_u32 s98, s42, 0x80
	s_addc_u32 s99, s43, 0
	s_add_u32 s100, s42, 0x104080
	s_addc_u32 s101, s43, 0
	s_add_i32 m0, s22, 0xc000
	s_nop 0
	global_load_lds_dwordx4 v134, s[100:101]
	s_add_i32 m0, s22, 0xe000
	s_nop 0
	global_load_lds_dwordx4 v130, s[100:101]
	s_mov_b32 m0, s52
	s_nop 0
	global_load_lds_dwordx4 v134, s[98:99]
	s_mov_b32 m0, s53
	s_nop 0
	global_load_lds_dwordx4 v130, s[98:99]
	s_and_b64 vcc, exec, s[40:41]
	s_cbranch_vccz .LBB0_1136
	s_barrier
